# clear the 128 GEMM accumulators with 64 v_mov_b64 instead of 128 v_mov_b32 per unit (14 sites)
# speedup vs baseline: 1.0066x; 1.0066x over previous
; template <class Epi, class Sched>
; __device__ __forceinline__ void gemm_phase(LAS unsigned char* lds, const Gemm g, const Sched& S, const Epi& E) {
;     ...
; #pragma unroll
;     for (int a = 0; a < 2; ++a)
; #pragma unroll
;         for (int b = 0; b < 2; ++b)
; #pragma unroll
;             for (int m = 0; m < 4; ++m)
; #pragma unroll
;                 for (int n = 0; n < 2; ++n) acc[a][b][m][n] = (f32x4){0.f, 0.f, 0.f, 0.f};
;     ...
; #pragma unroll
;         for (int a = 0; a < 2; ++a)
; #pragma unroll
;             for (int b = 0; b < 2; ++b)
; #pragma unroll
;                 for (int m = 0; m < 4; ++m)
; #pragma unroll
;                     for (int n = 0; n < 2; ++n) acc[a][b][m][n] = (f32x4){0.f, 0.f, 0.f, 0.f};
.LBB0_176:
	s_waitcnt vmcnt(0)
	v_mov_b64_e32 v[2:3], 0
	v_mov_b64_e32 v[4:5], 0
	v_mov_b64_e32 v[6:7], 0
	v_mov_b64_e32 v[8:9], 0
	v_mov_b64_e32 v[10:11], 0
	v_mov_b64_e32 v[12:13], 0
	v_mov_b64_e32 v[14:15], 0
	v_mov_b64_e32 v[16:17], 0
	v_mov_b64_e32 v[18:19], 0
	v_mov_b64_e32 v[20:21], 0
	v_mov_b64_e32 v[22:23], 0
	v_mov_b64_e32 v[24:25], 0
	v_mov_b64_e32 v[26:27], 0
	v_mov_b64_e32 v[28:29], 0
	v_mov_b64_e32 v[30:31], 0
	v_mov_b64_e32 v[32:33], 0
	v_mov_b64_e32 v[34:35], 0
	v_mov_b64_e32 v[36:37], 0
	v_mov_b64_e32 v[38:39], 0
	v_mov_b64_e32 v[40:41], 0
	v_mov_b64_e32 v[42:43], 0
	v_mov_b64_e32 v[44:45], 0
	v_mov_b64_e32 v[46:47], 0
	v_mov_b64_e32 v[48:49], 0
	v_mov_b64_e32 v[50:51], 0
	v_mov_b64_e32 v[52:53], 0
	v_mov_b64_e32 v[54:55], 0
	v_mov_b64_e32 v[56:57], 0
	v_mov_b64_e32 v[58:59], 0
	v_mov_b64_e32 v[60:61], 0
	v_mov_b64_e32 v[62:63], 0
	v_mov_b64_e32 v[64:65], 0
	v_mov_b64_e32 v[66:67], 0
	v_mov_b64_e32 v[68:69], 0
	v_mov_b64_e32 v[70:71], 0
	v_mov_b64_e32 v[72:73], 0
	v_mov_b64_e32 v[74:75], 0
	v_mov_b64_e32 v[76:77], 0
	v_mov_b64_e32 v[78:79], 0
	v_mov_b64_e32 v[80:81], 0
	v_mov_b64_e32 v[82:83], 0
	v_mov_b64_e32 v[84:85], 0
	v_mov_b64_e32 v[86:87], 0
	v_mov_b64_e32 v[88:89], 0
	v_mov_b64_e32 v[90:91], 0
	v_mov_b64_e32 v[92:93], 0
	v_mov_b64_e32 v[94:95], 0
	v_mov_b64_e32 v[96:97], 0
	v_mov_b64_e32 v[98:99], 0
	v_mov_b64_e32 v[100:101], 0
	v_mov_b64_e32 v[102:103], 0
	v_mov_b64_e32 v[104:105], 0
	v_mov_b64_e32 v[106:107], 0
	v_mov_b64_e32 v[108:109], 0
	v_mov_b64_e32 v[110:111], 0
	v_mov_b64_e32 v[112:113], 0
	v_mov_b64_e32 v[114:115], 0
	v_mov_b64_e32 v[116:117], 0
	v_mov_b64_e32 v[118:119], 0
	v_mov_b64_e32 v[120:121], 0
	v_mov_b64_e32 v[122:123], 0
	v_mov_b64_e32 v[124:125], 0
	v_mov_b64_e32 v[126:127], 0
	v_mov_b64_e32 v[128:129], 0
	s_andn2_b64 vcc, exec, s[56:57]
	s_cbranch_vccnz .LBB0_179
	s_add_u32 s15, s0, 0x100
	s_addc_u32 s16, s1, 0
	s_add_u32 s0, s64, 0x80
	v_mov_b64_e32 v[2:3], 0
	v_mov_b64_e32 v[4:5], 0
	v_mov_b64_e32 v[6:7], 0
	v_mov_b64_e32 v[8:9], 0
	v_mov_b64_e32 v[10:11], 0
	v_mov_b64_e32 v[12:13], 0
	v_mov_b64_e32 v[14:15], 0
	v_mov_b64_e32 v[16:17], 0
	v_mov_b64_e32 v[18:19], 0
	v_mov_b64_e32 v[20:21], 0
	v_mov_b64_e32 v[22:23], 0
	v_mov_b64_e32 v[24:25], 0
	v_mov_b64_e32 v[26:27], 0
	v_mov_b64_e32 v[28:29], 0
	v_mov_b64_e32 v[30:31], 0
	v_mov_b64_e32 v[32:33], 0
	v_mov_b64_e32 v[34:35], 0
	v_mov_b64_e32 v[36:37], 0
	v_mov_b64_e32 v[38:39], 0
	v_mov_b64_e32 v[40:41], 0
	v_mov_b64_e32 v[42:43], 0
	v_mov_b64_e32 v[44:45], 0
	v_mov_b64_e32 v[46:47], 0
	v_mov_b64_e32 v[48:49], 0
	v_mov_b64_e32 v[50:51], 0
	v_mov_b64_e32 v[52:53], 0
	v_mov_b64_e32 v[54:55], 0
	v_mov_b64_e32 v[56:57], 0
	v_mov_b64_e32 v[58:59], 0
	v_mov_b64_e32 v[60:61], 0
	v_mov_b64_e32 v[62:63], 0
	v_mov_b64_e32 v[64:65], 0
	v_mov_b64_e32 v[66:67], 0
	v_mov_b64_e32 v[68:69], 0
	v_mov_b64_e32 v[70:71], 0
	v_mov_b64_e32 v[72:73], 0
	v_mov_b64_e32 v[74:75], 0
	v_mov_b64_e32 v[76:77], 0
	v_mov_b64_e32 v[78:79], 0
	v_mov_b64_e32 v[80:81], 0
	v_mov_b64_e32 v[82:83], 0
	v_mov_b64_e32 v[84:85], 0
	v_mov_b64_e32 v[86:87], 0
	v_mov_b64_e32 v[88:89], 0
	v_mov_b64_e32 v[90:91], 0
	v_mov_b64_e32 v[92:93], 0
	v_mov_b64_e32 v[94:95], 0
	v_mov_b64_e32 v[96:97], 0
	v_mov_b64_e32 v[98:99], 0
	v_mov_b64_e32 v[100:101], 0
	v_mov_b64_e32 v[102:103], 0
	v_mov_b64_e32 v[104:105], 0
	v_mov_b64_e32 v[106:107], 0
	v_mov_b64_e32 v[108:109], 0
	v_mov_b64_e32 v[110:111], 0
	v_mov_b64_e32 v[112:113], 0
	v_mov_b64_e32 v[114:115], 0
	v_mov_b64_e32 v[116:117], 0
	v_mov_b64_e32 v[118:119], 0
	v_mov_b64_e32 v[120:121], 0
	v_mov_b64_e32 v[122:123], 0
	v_mov_b64_e32 v[124:125], 0
	v_mov_b64_e32 v[126:127], 0
	v_mov_b64_e32 v[128:129], 0
	s_addc_u32 s1, s65, 0
	s_mov_b32 s28, 0

; template <class Epi, class Sched>
; __device__ __forceinline__ void gemm_phase(LAS unsigned char* lds, const Gemm g, const Sched& S, const Epi& E) {
;     ...
; #pragma unroll
;     for (int a = 0; a < 2; ++a)
; #pragma unroll
;         for (int b = 0; b < 2; ++b)
; #pragma unroll
;             for (int m = 0; m < 4; ++m)
; #pragma unroll
;                 for (int n = 0; n < 2; ++n) acc[a][b][m][n] = (f32x4){0.f, 0.f, 0.f, 0.f};
;     ...
; #pragma unroll
;         for (int a = 0; a < 2; ++a)
; #pragma unroll
;             for (int b = 0; b < 2; ++b)
; #pragma unroll
;                 for (int m = 0; m < 4; ++m)
; #pragma unroll
;                     for (int n = 0; n < 2; ++n) acc[a][b][m][n] = (f32x4){0.f, 0.f, 0.f, 0.f};
.LBB0_294:
	v_mov_b32_e32 v209, 0
	s_andn2_b64 vcc, exec, s[62:63]
	v_mov_b32_e32 v208, 0
	v_mov_b32_e32 v211, 0
	v_mov_b32_e32 v210, 0
	v_mov_b32_e32 v213, 0
	v_mov_b32_e32 v212, 0
	v_mov_b32_e32 v215, 0
	v_mov_b32_e32 v214, 0
	v_mov_b32_e32 v185, 0
	v_mov_b32_e32 v184, 0
	v_mov_b32_e32 v183, 0
	v_mov_b32_e32 v182, 0
	v_mov_b32_e32 v181, 0
	v_mov_b32_e32 v180, 0
	v_mov_b32_e32 v179, 0
	v_mov_b32_e32 v178, 0
	v_mov_b32_e32 v169, 0
	v_mov_b32_e32 v168, 0
	v_mov_b32_e32 v167, 0
	v_mov_b32_e32 v166, 0
	v_mov_b32_e32 v165, 0
	v_mov_b32_e32 v164, 0
	v_mov_b32_e32 v163, 0
	v_mov_b32_e32 v162, 0
	v_mov_b32_e32 v151, 0
	v_mov_b32_e32 v150, 0
	v_mov_b32_e32 v149, 0
	v_mov_b32_e32 v148, 0
	v_mov_b32_e32 v147, 0
	v_mov_b32_e32 v146, 0
	v_mov_b32_e32 v145, 0
	v_mov_b32_e32 v144, 0
	v_mov_b32_e32 v193, 0
	v_mov_b32_e32 v192, 0
	v_mov_b32_e32 v191, 0
	v_mov_b32_e32 v190, 0
	v_mov_b32_e32 v189, 0
	v_mov_b32_e32 v188, 0
	v_mov_b32_e32 v187, 0
	v_mov_b32_e32 v186, 0
	v_mov_b32_e32 v177, 0
	v_mov_b32_e32 v176, 0
	v_mov_b32_e32 v175, 0
	v_mov_b32_e32 v174, 0
	v_mov_b32_e32 v173, 0
	v_mov_b32_e32 v172, 0
	v_mov_b32_e32 v171, 0
	v_mov_b32_e32 v170, 0
	v_mov_b32_e32 v161, 0
	v_mov_b32_e32 v160, 0
	v_mov_b32_e32 v159, 0
	v_mov_b32_e32 v158, 0
	v_mov_b32_e32 v157, 0
	v_mov_b32_e32 v156, 0
	v_mov_b32_e32 v155, 0
	v_mov_b32_e32 v154, 0
	v_mov_b32_e32 v143, 0
	v_mov_b32_e32 v142, 0
	v_mov_b32_e32 v141, 0
	v_mov_b32_e32 v140, 0
	v_mov_b32_e32 v129, 0
	v_mov_b32_e32 v128, 0
	v_mov_b32_e32 v127, 0
	v_mov_b32_e32 v126, 0
	v_mov_b32_e32 v125, 0
	v_mov_b32_e32 v124, 0
	v_mov_b32_e32 v123, 0
	v_mov_b32_e32 v122, 0
	v_mov_b32_e32 v121, 0
	v_mov_b32_e32 v120, 0
	v_mov_b32_e32 v119, 0
	v_mov_b32_e32 v118, 0
	v_mov_b32_e32 v109, 0
	v_mov_b32_e32 v108, 0
	v_mov_b32_e32 v107, 0
	v_mov_b32_e32 v106, 0
	v_mov_b32_e32 v105, 0
	v_mov_b32_e32 v104, 0
	v_mov_b32_e32 v103, 0
	v_mov_b32_e32 v102, 0
	v_mov_b32_e32 v93, 0
	v_mov_b32_e32 v92, 0
	v_mov_b32_e32 v91, 0
	v_mov_b32_e32 v90, 0
	v_mov_b32_e32 v89, 0
	v_mov_b32_e32 v88, 0
	v_mov_b32_e32 v87, 0
	v_mov_b32_e32 v86, 0
	v_mov_b32_e32 v77, 0
	v_mov_b32_e32 v76, 0
	v_mov_b32_e32 v75, 0
	v_mov_b32_e32 v74, 0
	v_mov_b32_e32 v73, 0
	v_mov_b32_e32 v72, 0
	v_mov_b32_e32 v71, 0
	v_mov_b32_e32 v70, 0
	v_mov_b32_e32 v117, 0
	v_mov_b32_e32 v116, 0
	v_mov_b32_e32 v115, 0
	v_mov_b32_e32 v114, 0
	v_mov_b32_e32 v113, 0
	v_mov_b32_e32 v112, 0
	v_mov_b32_e32 v111, 0
	v_mov_b32_e32 v110, 0
	v_mov_b32_e32 v101, 0
	v_mov_b32_e32 v100, 0
	v_mov_b32_e32 v99, 0
	v_mov_b32_e32 v98, 0
	v_mov_b32_e32 v97, 0
	v_mov_b32_e32 v96, 0
	v_mov_b32_e32 v95, 0
	v_mov_b32_e32 v94, 0
	v_mov_b32_e32 v85, 0
	v_mov_b32_e32 v84, 0
	v_mov_b32_e32 v83, 0
	v_mov_b32_e32 v82, 0
	v_mov_b32_e32 v81, 0
	v_mov_b32_e32 v80, 0
	v_mov_b32_e32 v79, 0
	v_mov_b32_e32 v78, 0
	v_mov_b32_e32 v69, 0
	v_mov_b32_e32 v68, 0
	v_mov_b32_e32 v67, 0
	v_mov_b32_e32 v66, 0
	v_mov_b32_e32 v65, 0
	v_mov_b32_e32 v64, 0
	v_mov_b32_e32 v63, 0
	v_mov_b32_e32 v62, 0
	s_cbranch_vccnz .LBB0_298
	s_add_u32 s15, s0, 0x100
	s_addc_u32 s16, s1, 0
	s_add_u32 s0, s38, 0x80
	v_mov_b64_e32 v[2:3], 0
	v_mov_b64_e32 v[4:5], 0
	v_mov_b64_e32 v[6:7], 0
	v_mov_b64_e32 v[8:9], 0
	v_mov_b64_e32 v[10:11], 0
	v_mov_b64_e32 v[12:13], 0
	v_mov_b64_e32 v[14:15], 0
	v_mov_b64_e32 v[16:17], 0
	v_mov_b64_e32 v[18:19], 0
	v_mov_b64_e32 v[20:21], 0
	v_mov_b64_e32 v[22:23], 0
	v_mov_b64_e32 v[24:25], 0
	v_mov_b64_e32 v[26:27], 0
	v_mov_b64_e32 v[28:29], 0
	v_mov_b64_e32 v[30:31], 0
	v_mov_b64_e32 v[32:33], 0
	v_mov_b64_e32 v[34:35], 0
	v_mov_b64_e32 v[36:37], 0
	v_mov_b64_e32 v[38:39], 0
	v_mov_b64_e32 v[40:41], 0
	v_mov_b64_e32 v[42:43], 0
	v_mov_b64_e32 v[44:45], 0
	v_mov_b64_e32 v[46:47], 0
	v_mov_b64_e32 v[48:49], 0
	v_mov_b64_e32 v[50:51], 0
	v_mov_b64_e32 v[52:53], 0
	v_mov_b64_e32 v[54:55], 0
	v_mov_b64_e32 v[56:57], 0
	v_mov_b64_e32 v[58:59], 0
	v_mov_b64_e32 v[60:61], 0
	v_mov_b64_e32 v[62:63], 0
	v_mov_b64_e32 v[64:65], 0
	v_mov_b64_e32 v[66:67], 0
	v_mov_b64_e32 v[68:69], 0
	v_mov_b64_e32 v[70:71], 0
	v_mov_b64_e32 v[72:73], 0
	v_mov_b64_e32 v[74:75], 0
	v_mov_b64_e32 v[76:77], 0
	v_mov_b64_e32 v[78:79], 0
	v_mov_b64_e32 v[80:81], 0
	v_mov_b64_e32 v[82:83], 0
	v_mov_b64_e32 v[84:85], 0
	v_mov_b64_e32 v[86:87], 0
	v_mov_b64_e32 v[88:89], 0
	v_mov_b64_e32 v[90:91], 0
	v_mov_b64_e32 v[92:93], 0
	v_mov_b64_e32 v[94:95], 0
	v_mov_b64_e32 v[96:97], 0
	v_mov_b64_e32 v[98:99], 0
	v_mov_b64_e32 v[100:101], 0
	v_mov_b64_e32 v[102:103], 0
	v_mov_b64_e32 v[104:105], 0
	v_mov_b64_e32 v[106:107], 0
	v_mov_b64_e32 v[108:109], 0
	v_mov_b64_e32 v[110:111], 0
	v_mov_b64_e32 v[112:113], 0
	v_mov_b64_e32 v[114:115], 0
	v_mov_b64_e32 v[116:117], 0
	v_mov_b64_e32 v[118:119], 0
	v_mov_b64_e32 v[120:121], 0
	v_mov_b64_e32 v[122:123], 0
	v_mov_b64_e32 v[124:125], 0
	v_mov_b64_e32 v[126:127], 0
	v_mov_b64_e32 v[128:129], 0
	s_addc_u32 s1, s39, 0
	s_mov_b32 s28, 0

; template <class Epi, class Sched>
; __device__ __forceinline__ void gemm_phase(LAS unsigned char* lds, const Gemm g, const Sched& S, const Epi& E) {
;     ...
; #pragma unroll
;     for (int a = 0; a < 2; ++a)
; #pragma unroll
;         for (int b = 0; b < 2; ++b)
; #pragma unroll
;             for (int m = 0; m < 4; ++m)
; #pragma unroll
;                 for (int n = 0; n < 2; ++n) acc[a][b][m][n] = (f32x4){0.f, 0.f, 0.f, 0.f};
;     ...
; #pragma unroll
;         for (int a = 0; a < 2; ++a)
; #pragma unroll
;             for (int b = 0; b < 2; ++b)
; #pragma unroll
;                 for (int m = 0; m < 4; ++m)
; #pragma unroll
;                     for (int n = 0; n < 2; ++n) acc[a][b][m][n] = (f32x4){0.f, 0.f, 0.f, 0.f};
.LBB0_426:
	s_waitcnt vmcnt(0)
	v_mov_b64_e32 v[2:3], 0
	v_mov_b64_e32 v[4:5], 0
	v_mov_b64_e32 v[6:7], 0
	v_mov_b64_e32 v[8:9], 0
	v_mov_b64_e32 v[10:11], 0
	v_mov_b64_e32 v[12:13], 0
	v_mov_b64_e32 v[14:15], 0
	v_mov_b64_e32 v[16:17], 0
	v_mov_b64_e32 v[18:19], 0
	v_mov_b64_e32 v[20:21], 0
	v_mov_b64_e32 v[22:23], 0
	v_mov_b64_e32 v[24:25], 0
	v_mov_b64_e32 v[26:27], 0
	v_mov_b64_e32 v[28:29], 0
	v_mov_b64_e32 v[30:31], 0
	v_mov_b64_e32 v[32:33], 0
	v_mov_b64_e32 v[34:35], 0
	v_mov_b64_e32 v[36:37], 0
	v_mov_b64_e32 v[38:39], 0
	v_mov_b64_e32 v[40:41], 0
	v_mov_b64_e32 v[42:43], 0
	v_mov_b64_e32 v[44:45], 0
	v_mov_b64_e32 v[46:47], 0
	v_mov_b64_e32 v[48:49], 0
	v_mov_b64_e32 v[50:51], 0
	v_mov_b64_e32 v[52:53], 0
	v_mov_b64_e32 v[54:55], 0
	v_mov_b64_e32 v[56:57], 0
	v_mov_b64_e32 v[58:59], 0
	v_mov_b64_e32 v[60:61], 0
	v_mov_b64_e32 v[62:63], 0
	v_mov_b64_e32 v[64:65], 0
	v_mov_b64_e32 v[66:67], 0
	v_mov_b64_e32 v[68:69], 0
	v_mov_b64_e32 v[70:71], 0
	v_mov_b64_e32 v[72:73], 0
	v_mov_b64_e32 v[74:75], 0
	v_mov_b64_e32 v[76:77], 0
	v_mov_b64_e32 v[78:79], 0
	v_mov_b64_e32 v[80:81], 0
	v_mov_b64_e32 v[82:83], 0
	v_mov_b64_e32 v[84:85], 0
	v_mov_b64_e32 v[86:87], 0
	v_mov_b64_e32 v[88:89], 0
	v_mov_b64_e32 v[90:91], 0
	v_mov_b64_e32 v[92:93], 0
	v_mov_b64_e32 v[94:95], 0
	v_mov_b64_e32 v[96:97], 0
	v_mov_b64_e32 v[98:99], 0
	v_mov_b64_e32 v[100:101], 0
	v_mov_b64_e32 v[102:103], 0
	v_mov_b64_e32 v[104:105], 0
	v_mov_b64_e32 v[106:107], 0
	v_mov_b64_e32 v[108:109], 0
	v_mov_b64_e32 v[110:111], 0
	v_mov_b64_e32 v[112:113], 0
	v_mov_b64_e32 v[114:115], 0
	v_mov_b64_e32 v[116:117], 0
	v_mov_b64_e32 v[118:119], 0
	v_mov_b64_e32 v[120:121], 0
	v_mov_b64_e32 v[122:123], 0
	v_mov_b64_e32 v[124:125], 0
	v_mov_b64_e32 v[126:127], 0
	v_mov_b64_e32 v[128:129], 0
	s_andn2_b64 vcc, exec, s[60:61]
	s_cbranch_vccnz .LBB0_429
	s_add_u32 s15, s0, 0x100
	s_addc_u32 s16, s1, 0
	s_add_u32 s0, s38, 0x80
	v_mov_b64_e32 v[2:3], 0
	v_mov_b64_e32 v[4:5], 0
	v_mov_b64_e32 v[6:7], 0
	v_mov_b64_e32 v[8:9], 0
	v_mov_b64_e32 v[10:11], 0
	v_mov_b64_e32 v[12:13], 0
	v_mov_b64_e32 v[14:15], 0
	v_mov_b64_e32 v[16:17], 0
	v_mov_b64_e32 v[18:19], 0
	v_mov_b64_e32 v[20:21], 0
	v_mov_b64_e32 v[22:23], 0
	v_mov_b64_e32 v[24:25], 0
	v_mov_b64_e32 v[26:27], 0
	v_mov_b64_e32 v[28:29], 0
	v_mov_b64_e32 v[30:31], 0
	v_mov_b64_e32 v[32:33], 0
	v_mov_b64_e32 v[34:35], 0
	v_mov_b64_e32 v[36:37], 0
	v_mov_b64_e32 v[38:39], 0
	v_mov_b64_e32 v[40:41], 0
	v_mov_b64_e32 v[42:43], 0
	v_mov_b64_e32 v[44:45], 0
	v_mov_b64_e32 v[46:47], 0
	v_mov_b64_e32 v[48:49], 0
	v_mov_b64_e32 v[50:51], 0
	v_mov_b64_e32 v[52:53], 0
	v_mov_b64_e32 v[54:55], 0
	v_mov_b64_e32 v[56:57], 0
	v_mov_b64_e32 v[58:59], 0
	v_mov_b64_e32 v[60:61], 0
	v_mov_b64_e32 v[62:63], 0
	v_mov_b64_e32 v[64:65], 0
	v_mov_b64_e32 v[66:67], 0
	v_mov_b64_e32 v[68:69], 0
	v_mov_b64_e32 v[70:71], 0
	v_mov_b64_e32 v[72:73], 0
	v_mov_b64_e32 v[74:75], 0
	v_mov_b64_e32 v[76:77], 0
	v_mov_b64_e32 v[78:79], 0
	v_mov_b64_e32 v[80:81], 0
	v_mov_b64_e32 v[82:83], 0
	v_mov_b64_e32 v[84:85], 0
	v_mov_b64_e32 v[86:87], 0
	v_mov_b64_e32 v[88:89], 0
	v_mov_b64_e32 v[90:91], 0
	v_mov_b64_e32 v[92:93], 0
	v_mov_b64_e32 v[94:95], 0
	v_mov_b64_e32 v[96:97], 0
	v_mov_b64_e32 v[98:99], 0
	v_mov_b64_e32 v[100:101], 0
	v_mov_b64_e32 v[102:103], 0
	v_mov_b64_e32 v[104:105], 0
	v_mov_b64_e32 v[106:107], 0
	v_mov_b64_e32 v[108:109], 0
	v_mov_b64_e32 v[110:111], 0
	v_mov_b64_e32 v[112:113], 0
	v_mov_b64_e32 v[114:115], 0
	v_mov_b64_e32 v[116:117], 0
	v_mov_b64_e32 v[118:119], 0
	v_mov_b64_e32 v[120:121], 0
	v_mov_b64_e32 v[122:123], 0
	v_mov_b64_e32 v[124:125], 0
	v_mov_b64_e32 v[126:127], 0
	v_mov_b64_e32 v[128:129], 0
	s_addc_u32 s1, s39, 0
	s_mov_b32 s28, 0

; template <class Epi, class Sched>
; __device__ __forceinline__ void gemm_phase(LAS unsigned char* lds, const Gemm g, const Sched& S, const Epi& E) {
;     ...
; #pragma unroll
;     for (int a = 0; a < 2; ++a)
; #pragma unroll
;         for (int b = 0; b < 2; ++b)
; #pragma unroll
;             for (int m = 0; m < 4; ++m)
; #pragma unroll
;                 for (int n = 0; n < 2; ++n) acc[a][b][m][n] = (f32x4){0.f, 0.f, 0.f, 0.f};
;     ...
; #pragma unroll
;         for (int a = 0; a < 2; ++a)
; #pragma unroll
;             for (int b = 0; b < 2; ++b)
; #pragma unroll
;                 for (int m = 0; m < 4; ++m)
; #pragma unroll
;                     for (int n = 0; n < 2; ++n) acc[a][b][m][n] = (f32x4){0.f, 0.f, 0.f, 0.f};
.LBB0_1438:
	s_waitcnt vmcnt(0)
	v_mov_b64_e32 v[2:3], 0
	v_mov_b64_e32 v[4:5], 0
	v_mov_b64_e32 v[6:7], 0
	v_mov_b64_e32 v[8:9], 0
	v_mov_b64_e32 v[10:11], 0
	v_mov_b64_e32 v[12:13], 0
	v_mov_b64_e32 v[14:15], 0
	v_mov_b64_e32 v[16:17], 0
	v_mov_b64_e32 v[18:19], 0
	v_mov_b64_e32 v[20:21], 0
	v_mov_b64_e32 v[22:23], 0
	v_mov_b64_e32 v[24:25], 0
	v_mov_b64_e32 v[26:27], 0
	v_mov_b64_e32 v[28:29], 0
	v_mov_b64_e32 v[30:31], 0
	v_mov_b64_e32 v[32:33], 0
	v_mov_b64_e32 v[34:35], 0
	v_mov_b64_e32 v[36:37], 0
	v_mov_b64_e32 v[38:39], 0
	v_mov_b64_e32 v[40:41], 0
	v_mov_b64_e32 v[42:43], 0
	v_mov_b64_e32 v[44:45], 0
	v_mov_b64_e32 v[46:47], 0
	v_mov_b64_e32 v[48:49], 0
	v_mov_b64_e32 v[50:51], 0
	v_mov_b64_e32 v[52:53], 0
	v_mov_b64_e32 v[54:55], 0
	v_mov_b64_e32 v[56:57], 0
	v_mov_b64_e32 v[58:59], 0
	v_mov_b64_e32 v[60:61], 0
	v_mov_b64_e32 v[62:63], 0
	v_mov_b64_e32 v[64:65], 0
	v_mov_b64_e32 v[66:67], 0
	v_mov_b64_e32 v[68:69], 0
	v_mov_b64_e32 v[70:71], 0
	v_mov_b64_e32 v[72:73], 0
	v_mov_b64_e32 v[74:75], 0
	v_mov_b64_e32 v[76:77], 0
	v_mov_b64_e32 v[78:79], 0
	v_mov_b64_e32 v[80:81], 0
	v_mov_b64_e32 v[82:83], 0
	v_mov_b64_e32 v[84:85], 0
	v_mov_b64_e32 v[86:87], 0
	v_mov_b64_e32 v[88:89], 0
	v_mov_b64_e32 v[90:91], 0
	v_mov_b64_e32 v[92:93], 0
	v_mov_b64_e32 v[94:95], 0
	v_mov_b64_e32 v[96:97], 0
	v_mov_b64_e32 v[98:99], 0
	v_mov_b64_e32 v[100:101], 0
	v_mov_b64_e32 v[102:103], 0
	v_mov_b64_e32 v[104:105], 0
	v_mov_b64_e32 v[106:107], 0
	v_mov_b64_e32 v[108:109], 0
	v_mov_b64_e32 v[110:111], 0
	v_mov_b64_e32 v[112:113], 0
	v_mov_b64_e32 v[114:115], 0
	v_mov_b64_e32 v[116:117], 0
	v_mov_b64_e32 v[118:119], 0
	v_mov_b64_e32 v[120:121], 0
	v_mov_b64_e32 v[122:123], 0
	v_mov_b64_e32 v[124:125], 0
	v_mov_b64_e32 v[126:127], 0
	v_mov_b64_e32 v[128:129], 0
	s_andn2_b64 vcc, exec, s[64:65]
	s_cbranch_vccnz .LBB0_1441
	s_add_u32 s15, s0, 0x100
	s_addc_u32 s16, s1, 0
	s_add_u32 s0, s38, 0x80
	v_mov_b64_e32 v[2:3], 0
	v_mov_b64_e32 v[4:5], 0
	v_mov_b64_e32 v[6:7], 0
	v_mov_b64_e32 v[8:9], 0
	v_mov_b64_e32 v[10:11], 0
	v_mov_b64_e32 v[12:13], 0
	v_mov_b64_e32 v[14:15], 0
	v_mov_b64_e32 v[16:17], 0
	v_mov_b64_e32 v[18:19], 0
	v_mov_b64_e32 v[20:21], 0
	v_mov_b64_e32 v[22:23], 0
	v_mov_b64_e32 v[24:25], 0
	v_mov_b64_e32 v[26:27], 0
	v_mov_b64_e32 v[28:29], 0
	v_mov_b64_e32 v[30:31], 0
	v_mov_b64_e32 v[32:33], 0
	v_mov_b64_e32 v[34:35], 0
	v_mov_b64_e32 v[36:37], 0
	v_mov_b64_e32 v[38:39], 0
	v_mov_b64_e32 v[40:41], 0
	v_mov_b64_e32 v[42:43], 0
	v_mov_b64_e32 v[44:45], 0
	v_mov_b64_e32 v[46:47], 0
	v_mov_b64_e32 v[48:49], 0
	v_mov_b64_e32 v[50:51], 0
	v_mov_b64_e32 v[52:53], 0
	v_mov_b64_e32 v[54:55], 0
	v_mov_b64_e32 v[56:57], 0
	v_mov_b64_e32 v[58:59], 0
	v_mov_b64_e32 v[60:61], 0
	v_mov_b64_e32 v[62:63], 0
	v_mov_b64_e32 v[64:65], 0
	v_mov_b64_e32 v[66:67], 0
	v_mov_b64_e32 v[68:69], 0
	v_mov_b64_e32 v[70:71], 0
	v_mov_b64_e32 v[72:73], 0
	v_mov_b64_e32 v[74:75], 0
	v_mov_b64_e32 v[76:77], 0
	v_mov_b64_e32 v[78:79], 0
	v_mov_b64_e32 v[80:81], 0
	v_mov_b64_e32 v[82:83], 0
	v_mov_b64_e32 v[84:85], 0
	v_mov_b64_e32 v[86:87], 0
	v_mov_b64_e32 v[88:89], 0
	v_mov_b64_e32 v[90:91], 0
	v_mov_b64_e32 v[92:93], 0
	v_mov_b64_e32 v[94:95], 0
	v_mov_b64_e32 v[96:97], 0
	v_mov_b64_e32 v[98:99], 0
	v_mov_b64_e32 v[100:101], 0
	v_mov_b64_e32 v[102:103], 0
	v_mov_b64_e32 v[104:105], 0
	v_mov_b64_e32 v[106:107], 0
	v_mov_b64_e32 v[108:109], 0
	v_mov_b64_e32 v[110:111], 0
	v_mov_b64_e32 v[112:113], 0
	v_mov_b64_e32 v[114:115], 0
	v_mov_b64_e32 v[116:117], 0
	v_mov_b64_e32 v[118:119], 0
	v_mov_b64_e32 v[120:121], 0
	v_mov_b64_e32 v[122:123], 0
	v_mov_b64_e32 v[124:125], 0
	v_mov_b64_e32 v[126:127], 0
	v_mov_b64_e32 v[128:129], 0
	s_addc_u32 s1, s39, 0
	s_mov_b32 s28, 0

; #define PG8_BAR __builtin_amdgcn_s_barrier()
; template <class Epi, class Sched>
; __device__ __forceinline__ void gemm_phase(LAS unsigned char* lds, const Gemm g, const Sched& S, const Epi& E) {
;     ...
; #pragma unroll
;         for (int a = 0; a < 2; ++a)
; #pragma unroll
;             for (int b = 0; b < 2; ++b)
; #pragma unroll
;                 for (int m = 0; m < 4; ++m)
; #pragma unroll
;                     for (int n = 0; n < 2; ++n) acc[a][b][m][n] = (f32x4){0.f, 0.f, 0.f, 0.f};
;         cur = nxt; cA = nA; cB = nB; ++ui;
;         if (wr == 1) PG8_BAR;
;     }
.LBB0_1774:
	s_waitcnt vmcnt(0)
	v_mov_b64_e32 v[2:3], 0
	v_mov_b64_e32 v[4:5], 0
	v_mov_b64_e32 v[6:7], 0
	v_mov_b64_e32 v[8:9], 0
	v_mov_b64_e32 v[10:11], 0
	v_mov_b64_e32 v[12:13], 0
	v_mov_b64_e32 v[14:15], 0
	v_mov_b64_e32 v[16:17], 0
	v_mov_b64_e32 v[18:19], 0
	v_mov_b64_e32 v[20:21], 0
	v_mov_b64_e32 v[22:23], 0
	v_mov_b64_e32 v[24:25], 0
	v_mov_b64_e32 v[26:27], 0
	v_mov_b64_e32 v[28:29], 0
	v_mov_b64_e32 v[30:31], 0
	v_mov_b64_e32 v[32:33], 0
	v_mov_b64_e32 v[34:35], 0
	v_mov_b64_e32 v[36:37], 0
	v_mov_b64_e32 v[38:39], 0
	v_mov_b64_e32 v[40:41], 0
	v_mov_b64_e32 v[42:43], 0
	v_mov_b64_e32 v[44:45], 0
	v_mov_b64_e32 v[46:47], 0
	v_mov_b64_e32 v[48:49], 0
	v_mov_b64_e32 v[50:51], 0
	v_mov_b64_e32 v[52:53], 0
	v_mov_b64_e32 v[54:55], 0
	v_mov_b64_e32 v[56:57], 0
	v_mov_b64_e32 v[58:59], 0
	v_mov_b64_e32 v[60:61], 0
	v_mov_b64_e32 v[62:63], 0
	v_mov_b64_e32 v[64:65], 0
	v_mov_b64_e32 v[66:67], 0
	v_mov_b64_e32 v[68:69], 0
	v_mov_b64_e32 v[70:71], 0
	v_mov_b64_e32 v[72:73], 0
	v_mov_b64_e32 v[74:75], 0
	v_mov_b64_e32 v[76:77], 0
	v_mov_b64_e32 v[78:79], 0
	v_mov_b64_e32 v[80:81], 0
	v_mov_b64_e32 v[82:83], 0
	v_mov_b64_e32 v[84:85], 0
	v_mov_b64_e32 v[86:87], 0
	v_mov_b64_e32 v[88:89], 0
	v_mov_b64_e32 v[90:91], 0
	v_mov_b64_e32 v[92:93], 0
	v_mov_b64_e32 v[94:95], 0
	v_mov_b64_e32 v[96:97], 0
	v_mov_b64_e32 v[98:99], 0
	v_mov_b64_e32 v[100:101], 0
	v_mov_b64_e32 v[102:103], 0
	v_mov_b64_e32 v[104:105], 0
	v_mov_b64_e32 v[106:107], 0
	v_mov_b64_e32 v[108:109], 0
	v_mov_b64_e32 v[110:111], 0
	v_mov_b64_e32 v[112:113], 0
	v_mov_b64_e32 v[114:115], 0
	v_mov_b64_e32 v[116:117], 0
	v_mov_b64_e32 v[118:119], 0
	v_mov_b64_e32 v[120:121], 0
	v_mov_b64_e32 v[122:123], 0
	v_mov_b64_e32 v[124:125], 0
	v_mov_b64_e32 v[126:127], 0
	v_mov_b64_e32 v[128:129], 0
	s_andn2_b64 vcc, exec, s[62:63]
	s_cbranch_vccnz .LBB0_1778
	s_add_u32 s15, s0, 0x100
	s_addc_u32 s16, s1, 0
	s_add_u32 s0, s38, 0x80
	v_mov_b64_e32 v[2:3], 0
	v_mov_b64_e32 v[4:5], 0
	v_mov_b64_e32 v[6:7], 0
	v_mov_b64_e32 v[8:9], 0
	v_mov_b64_e32 v[10:11], 0
	v_mov_b64_e32 v[12:13], 0
	v_mov_b64_e32 v[14:15], 0
	v_mov_b64_e32 v[16:17], 0
	v_mov_b64_e32 v[18:19], 0
	v_mov_b64_e32 v[20:21], 0
	v_mov_b64_e32 v[22:23], 0
	v_mov_b64_e32 v[24:25], 0
	v_mov_b64_e32 v[26:27], 0
	v_mov_b64_e32 v[28:29], 0
	v_mov_b64_e32 v[30:31], 0
	v_mov_b64_e32 v[32:33], 0
	v_mov_b64_e32 v[34:35], 0
	v_mov_b64_e32 v[36:37], 0
	v_mov_b64_e32 v[38:39], 0
	v_mov_b64_e32 v[40:41], 0
	v_mov_b64_e32 v[42:43], 0
	v_mov_b64_e32 v[44:45], 0
	v_mov_b64_e32 v[46:47], 0
	v_mov_b64_e32 v[48:49], 0
	v_mov_b64_e32 v[50:51], 0
	v_mov_b64_e32 v[52:53], 0
	v_mov_b64_e32 v[54:55], 0
	v_mov_b64_e32 v[56:57], 0
	v_mov_b64_e32 v[58:59], 0
	v_mov_b64_e32 v[60:61], 0
	v_mov_b64_e32 v[62:63], 0
	v_mov_b64_e32 v[64:65], 0
	v_mov_b64_e32 v[66:67], 0
	v_mov_b64_e32 v[68:69], 0
	v_mov_b64_e32 v[70:71], 0
	v_mov_b64_e32 v[72:73], 0
	v_mov_b64_e32 v[74:75], 0
	v_mov_b64_e32 v[76:77], 0
	v_mov_b64_e32 v[78:79], 0
	v_mov_b64_e32 v[80:81], 0
	v_mov_b64_e32 v[82:83], 0
	v_mov_b64_e32 v[84:85], 0
	v_mov_b64_e32 v[86:87], 0
	v_mov_b64_e32 v[88:89], 0
	v_mov_b64_e32 v[90:91], 0
	v_mov_b64_e32 v[92:93], 0
	v_mov_b64_e32 v[94:95], 0
	v_mov_b64_e32 v[96:97], 0
	v_mov_b64_e32 v[98:99], 0
	v_mov_b64_e32 v[100:101], 0
	v_mov_b64_e32 v[102:103], 0
	v_mov_b64_e32 v[104:105], 0
	v_mov_b64_e32 v[106:107], 0
	v_mov_b64_e32 v[108:109], 0
	v_mov_b64_e32 v[110:111], 0
	v_mov_b64_e32 v[112:113], 0
	v_mov_b64_e32 v[114:115], 0
	v_mov_b64_e32 v[116:117], 0
	v_mov_b64_e32 v[118:119], 0
	v_mov_b64_e32 v[120:121], 0
	v_mov_b64_e32 v[122:123], 0
	v_mov_b64_e32 v[124:125], 0
	v_mov_b64_e32 v[126:127], 0
	v_mov_b64_e32 v[128:129], 0
	s_addc_u32 s1, s39, 0
	s_mov_b32 s28, 0

; #define PG8_BAR __builtin_amdgcn_s_barrier()
; template <class Epi, class Sched>
; __device__ __forceinline__ void gemm_phase(LAS unsigned char* lds, const Gemm g, const Sched& S, const Epi& E) {
;     ...
; #pragma unroll
;         for (int a = 0; a < 2; ++a)
; #pragma unroll
;             for (int b = 0; b < 2; ++b)
; #pragma unroll
;                 for (int m = 0; m < 4; ++m)
; #pragma unroll
;                     for (int n = 0; n < 2; ++n) acc[a][b][m][n] = (f32x4){0.f, 0.f, 0.f, 0.f};
;         cur = nxt; cA = nA; cB = nB; ++ui;
;         if (wr == 1) PG8_BAR;
;     }
.LBB0_2024:
	v_mov_b32_e32 v209, 0
	s_andn2_b64 vcc, exec, s[58:59]
	v_mov_b32_e32 v208, 0
	v_mov_b32_e32 v211, 0
	v_mov_b32_e32 v210, 0
	v_mov_b32_e32 v213, 0
	v_mov_b32_e32 v212, 0
	v_mov_b32_e32 v215, 0
	v_mov_b32_e32 v214, 0
	v_mov_b32_e32 v185, 0
	v_mov_b32_e32 v184, 0
	v_mov_b32_e32 v183, 0
	v_mov_b32_e32 v182, 0
	v_mov_b32_e32 v181, 0
	v_mov_b32_e32 v180, 0
	v_mov_b32_e32 v179, 0
	v_mov_b32_e32 v178, 0
	v_mov_b32_e32 v169, 0
	v_mov_b32_e32 v168, 0
	v_mov_b32_e32 v167, 0
	v_mov_b32_e32 v166, 0
	v_mov_b32_e32 v165, 0
	v_mov_b32_e32 v164, 0
	v_mov_b32_e32 v163, 0
	v_mov_b32_e32 v162, 0
	v_mov_b32_e32 v151, 0
	v_mov_b32_e32 v150, 0
	v_mov_b32_e32 v149, 0
	v_mov_b32_e32 v148, 0
	v_mov_b32_e32 v147, 0
	v_mov_b32_e32 v146, 0
	v_mov_b32_e32 v145, 0
	v_mov_b32_e32 v144, 0
	v_mov_b32_e32 v193, 0
	v_mov_b32_e32 v192, 0
	v_mov_b32_e32 v191, 0
	v_mov_b32_e32 v190, 0
	v_mov_b32_e32 v189, 0
	v_mov_b32_e32 v188, 0
	v_mov_b32_e32 v187, 0
	v_mov_b32_e32 v186, 0
	v_mov_b32_e32 v177, 0
	v_mov_b32_e32 v176, 0
	v_mov_b32_e32 v175, 0
	v_mov_b32_e32 v174, 0
	v_mov_b32_e32 v173, 0
	v_mov_b32_e32 v172, 0
	v_mov_b32_e32 v171, 0
	v_mov_b32_e32 v170, 0
	v_mov_b32_e32 v161, 0
	v_mov_b32_e32 v160, 0
	v_mov_b32_e32 v159, 0
	v_mov_b32_e32 v158, 0
	v_mov_b32_e32 v157, 0
	v_mov_b32_e32 v156, 0
	v_mov_b32_e32 v155, 0
	v_mov_b32_e32 v154, 0
	v_mov_b32_e32 v143, 0
	v_mov_b32_e32 v142, 0
	v_mov_b32_e32 v141, 0
	v_mov_b32_e32 v140, 0
	v_mov_b32_e32 v129, 0
	v_mov_b32_e32 v128, 0
	v_mov_b32_e32 v127, 0
	v_mov_b32_e32 v126, 0
	v_mov_b32_e32 v125, 0
	v_mov_b32_e32 v124, 0
	v_mov_b32_e32 v123, 0
	v_mov_b32_e32 v122, 0
	v_mov_b32_e32 v121, 0
	v_mov_b32_e32 v120, 0
	v_mov_b32_e32 v119, 0
	v_mov_b32_e32 v118, 0
	v_mov_b32_e32 v109, 0
	v_mov_b32_e32 v108, 0
	v_mov_b32_e32 v107, 0
	v_mov_b32_e32 v106, 0
	v_mov_b32_e32 v105, 0
	v_mov_b32_e32 v104, 0
	v_mov_b32_e32 v103, 0
	v_mov_b32_e32 v102, 0
	v_mov_b32_e32 v93, 0
	v_mov_b32_e32 v92, 0
	v_mov_b32_e32 v91, 0
	v_mov_b32_e32 v90, 0
	v_mov_b32_e32 v89, 0
	v_mov_b32_e32 v88, 0
	v_mov_b32_e32 v87, 0
	v_mov_b32_e32 v86, 0
	v_mov_b32_e32 v77, 0
	v_mov_b32_e32 v76, 0
	v_mov_b32_e32 v75, 0
	v_mov_b32_e32 v74, 0
	v_mov_b32_e32 v73, 0
	v_mov_b32_e32 v72, 0
	v_mov_b32_e32 v71, 0
	v_mov_b32_e32 v70, 0
	v_mov_b32_e32 v117, 0
	v_mov_b32_e32 v116, 0
	v_mov_b32_e32 v115, 0
	v_mov_b32_e32 v114, 0
	v_mov_b32_e32 v113, 0
	v_mov_b32_e32 v112, 0
	v_mov_b32_e32 v111, 0
	v_mov_b32_e32 v110, 0
	v_mov_b32_e32 v101, 0
	v_mov_b32_e32 v100, 0
	v_mov_b32_e32 v99, 0
	v_mov_b32_e32 v98, 0
	v_mov_b32_e32 v97, 0
	v_mov_b32_e32 v96, 0
	v_mov_b32_e32 v95, 0
	v_mov_b32_e32 v94, 0
	v_mov_b32_e32 v85, 0
	v_mov_b32_e32 v84, 0
	v_mov_b32_e32 v83, 0
	v_mov_b32_e32 v82, 0
	v_mov_b32_e32 v81, 0
	v_mov_b32_e32 v80, 0
	v_mov_b32_e32 v79, 0
	v_mov_b32_e32 v78, 0
	v_mov_b32_e32 v69, 0
	v_mov_b32_e32 v68, 0
	v_mov_b32_e32 v67, 0
	v_mov_b32_e32 v66, 0
	v_mov_b32_e32 v65, 0
	v_mov_b32_e32 v64, 0
	v_mov_b32_e32 v63, 0
	v_mov_b32_e32 v62, 0
	s_cbranch_vccnz .LBB0_2028
	s_add_u32 s15, s0, 0x100
	s_addc_u32 s16, s1, 0
	s_add_u32 s0, s64, 0x80
	v_mov_b64_e32 v[2:3], 0
	v_mov_b64_e32 v[4:5], 0
	v_mov_b64_e32 v[6:7], 0
	v_mov_b64_e32 v[8:9], 0
	v_mov_b64_e32 v[10:11], 0
	v_mov_b64_e32 v[12:13], 0
	v_mov_b64_e32 v[14:15], 0
	v_mov_b64_e32 v[16:17], 0
	v_mov_b64_e32 v[18:19], 0
	v_mov_b64_e32 v[20:21], 0
	v_mov_b64_e32 v[22:23], 0
	v_mov_b64_e32 v[24:25], 0
	v_mov_b64_e32 v[26:27], 0
	v_mov_b64_e32 v[28:29], 0
	v_mov_b64_e32 v[30:31], 0
	v_mov_b64_e32 v[32:33], 0
	v_mov_b64_e32 v[34:35], 0
	v_mov_b64_e32 v[36:37], 0
	v_mov_b64_e32 v[38:39], 0
	v_mov_b64_e32 v[40:41], 0
	v_mov_b64_e32 v[42:43], 0
	v_mov_b64_e32 v[44:45], 0
	v_mov_b64_e32 v[46:47], 0
	v_mov_b64_e32 v[48:49], 0
	v_mov_b64_e32 v[50:51], 0
	v_mov_b64_e32 v[52:53], 0
	v_mov_b64_e32 v[54:55], 0
	v_mov_b64_e32 v[56:57], 0
	v_mov_b64_e32 v[58:59], 0
	v_mov_b64_e32 v[60:61], 0
	v_mov_b64_e32 v[62:63], 0
	v_mov_b64_e32 v[64:65], 0
	v_mov_b64_e32 v[66:67], 0
	v_mov_b64_e32 v[68:69], 0
	v_mov_b64_e32 v[70:71], 0
	v_mov_b64_e32 v[72:73], 0
	v_mov_b64_e32 v[74:75], 0
	v_mov_b64_e32 v[76:77], 0
	v_mov_b64_e32 v[78:79], 0
	v_mov_b64_e32 v[80:81], 0
	v_mov_b64_e32 v[82:83], 0
	v_mov_b64_e32 v[84:85], 0
	v_mov_b64_e32 v[86:87], 0
	v_mov_b64_e32 v[88:89], 0
	v_mov_b64_e32 v[90:91], 0
	v_mov_b64_e32 v[92:93], 0
	v_mov_b64_e32 v[94:95], 0
	v_mov_b64_e32 v[96:97], 0
	v_mov_b64_e32 v[98:99], 0
	v_mov_b64_e32 v[100:101], 0
	v_mov_b64_e32 v[102:103], 0
	v_mov_b64_e32 v[104:105], 0
	v_mov_b64_e32 v[106:107], 0
	v_mov_b64_e32 v[108:109], 0
	v_mov_b64_e32 v[110:111], 0
	v_mov_b64_e32 v[112:113], 0
	v_mov_b64_e32 v[114:115], 0
	v_mov_b64_e32 v[116:117], 0
	v_mov_b64_e32 v[118:119], 0
	v_mov_b64_e32 v[120:121], 0
	v_mov_b64_e32 v[122:123], 0
	v_mov_b64_e32 v[124:125], 0
	v_mov_b64_e32 v[126:127], 0
	v_mov_b64_e32 v[128:129], 0
	s_addc_u32 s1, s65, 0
	s_mov_b32 s28, 0
